# scan v2: v-slice loads cover whole lines, o tile leaves through a wave-private LDS transpose (16-byte full-line stores); on top of fragment-major ABUF/KDT
# speedup vs baseline: 1.0777x; 1.0128x over previous
.LBB0_1313:
	s_or_b64 exec, exec, s[0:1]
	s_add_u32 s6, s94, 0x2a402800
	s_addc_u32 s7, s95, 0
	s_cmpk_gt_u32 s2, 0x7f
	s_waitcnt lgkmcnt(0)
	s_barrier
	s_cbranch_scc1 .LBB0_1326
	s_and_b32 s76, s2, 7
	s_lshr_b32 s77, s2, 3
	s_lshr_b32 s78, s77, 3
	s_lshl_b32 s72, s76, 1
	s_add_u32 s72, s72, s78
	s_and_b32 s73, s77, 7
	s_lshr_b32 s74, s72, 2
	s_and_b32 s75, s72, 3
	s_mov_b32 s82, 0xbd020aec
	s_cmp_eq_u32 s75, 1
	s_cselect_b32 s82, 0xbc8102b3, s82
	s_cmp_eq_u32 s75, 2
	s_cselect_b32 s82, 0xbc0080ac, s82
	s_cmp_eq_u32 s75, 3
	s_cselect_b32 s82, 0xbb80402b, s82
	v_lshrrev_b32_e32 v210, 6, v198
	v_and_b32_e32 v211, 15, v198
	v_bfe_u32 v212, v198, 4, 2
	v_readfirstlane_b32 s71, v210
	v_lshl_or_b32 v213, v210, 4, v211
	v_add_u32_e32 v213, 1, v213
	v_cvt_f32_i32_e32 v213, v213
	v_mul_f32_e32 v213, s82, v213
	v_mul_f32_e32 v213, 0x3fb8aa3b, v213
	v_exp_f32_e32 v202, v213
	v_mov_b32_e32 v213, 0x43000000
	v_mul_f32_e32 v213, s82, v213
	v_mul_f32_e32 v213, 0x3fb8aa3b, v213
	v_exp_f32_e32 v204, v213
	s_nop 1
	v_mov_b32_e32 v203, v202
	v_mov_b32_e32 v205, v204
	v_lshlrev_b32_e32 v192, 4, v211
	v_lshl_add_u32 v192, v212, 8, v192
	v_lshlrev_b32_e32 v193, 11, v211
	v_lshl_add_u32 v193, v212, 4, v193
	v_and_b32_e32 v213, 63, v198
	v_lshrrev_b32_e32 v195, 3, v213
	v_and_b32_e32 v215, 7, v213
	v_mul_u32_u24_e32 v214, 144, v195
	v_lshl_add_u32 v215, v215, 4, v214
	v_and_b32_e32 v214, 7, v213
	v_lshlrev_b32_e32 v195, 12, v195
	v_lshl_add_u32 v195, v214, 4, v195
	v_add_u32_e32 v220, 0x8000, v195
	v_mul_u32_u24_e32 v214, 144, v211
	v_lshl_add_u32 v214, v212, 3, v214
	v_mul_u32_u24_e32 v213, 2304, v210
	v_add_u32_e32 v213, 102400, v213
	v_add_u32_e32 v214, v214, v213
	v_add_u32_e32 v215, v215, v213
	v_lshrrev_b32_e32 v213, 3, v198
	v_and_b32_e32 v194, 7, v198
	v_lshlrev_b32_e32 v194, 4, v194
	v_mul_u32_u24_e32 v201, 272, v213
	v_add_u32_e32 v201, v201, v194
	v_lshl_add_u32 v194, v213, 13, v194
	v_add_u32_e32 v201, 67584, v201
	v_mul_u32_u24_e32 v196, 528, v211
	v_lshl_add_u32 v200, v212, 3, v196
	v_lshl_add_u32 v200, v210, 6, v200
	v_add_u32_e32 v200, 33792, v200
	v_lshl_add_u32 v196, v212, 4, v196
	v_mul_u32_u24_e32 v197, 272, v211
	v_lshl_add_u32 v197, v212, 4, v197
	v_add_u32_e32 v197, 67584, v197
	v_lshlrev_b32_e32 v206, 13, v212
	v_lshl_add_u32 v206, v211, 2, v206
	v_add_u32_e32 v207, 2048, v206
	v_add_u32_e32 v208, 4096, v206
	v_add_u32_e32 v209, 6144, v206
	s_mov_b32 s76, 0x27402800
	s_lshl_b32 s77, s72, 20
	s_add_u32 s76, s76, s77
	s_lshl_b32 s77, s71, 12
	s_add_u32 s76, s76, s77
	s_add_u32 s62, s94, s76
	s_addc_u32 s63, s95, 0
	s_mov_b32 s76, 0x28403800
	s_lshl_b32 s77, s72, 21
	s_add_u32 s76, s76, s77
	s_lshl_b32 s77, s71, 13
	s_add_u32 s76, s76, s77
	s_add_u32 s64, s94, s76
	s_addc_u32 s65, s95, 0
	s_mov_b32 s76, 0x1a802800
	s_lshl_b32 s77, s74, 23
	s_add_u32 s76, s76, s77
	s_lshl_b32 s77, s71, 15
	s_add_u32 s76, s76, s77
	s_lshl_b32 s77, s75, 9
	s_add_u32 s76, s76, s77
	s_add_u32 s60, s94, s76
	s_addc_u32 s61, s95, 0
	s_mov_b32 s76, 0x23002800
	s_lshl_b32 s77, s72, 22
	s_add_u32 s76, s76, s77
	s_lshl_b32 s77, s73, 19
	s_add_u32 s76, s76, s77
	s_add_u32 s66, s94, s76
	s_addc_u32 s67, s95, 0
	s_mov_b32 s76, 0x2a402800
	s_lshl_b32 s77, s74, 24
	s_add_u32 s76, s76, s77
	s_lshl_b32 s77, s71, 16
	s_add_u32 s76, s76, s77
	s_lshl_b32 s77, s75, 10
	s_add_u32 s76, s76, s77
	s_lshl_b32 s77, s73, 7
	s_add_u32 s76, s76, s77
	s_add_u32 s68, s94, s76
	s_addc_u32 s69, s95, 0
	s_mov_b32 s76, 0x6500000
	s_lshl_b32 s77, s72, 19
	s_add_u32 s76, s76, s77
	s_lshl_b32 s77, s71, 16
	s_add_u32 s76, s76, s77
	s_lshl_b32 s77, s73, 8
	s_add_u32 s76, s76, s77
	s_add_u32 s44, s92, s76
	s_addc_u32 s45, s93, 0
	s_add_u32 s46, s44, 0x8000
	s_addc_u32 s47, s45, 0
	global_load_dwordx4 v[176:179], v194, s[66:67]
	global_load_dwordx4 v[180:183], v194, s[66:67] offset:128
	global_load_dwordx4 v[0:3], v193, s[60:61]
	global_load_dwordx4 v[4:7], v193, s[60:61] offset:64
	global_load_dwordx4 v[8:11], v193, s[60:61] offset:128
	global_load_dwordx4 v[12:15], v193, s[60:61] offset:192
	global_load_dwordx4 v[16:19], v193, s[60:61] offset:256
	global_load_dwordx4 v[20:23], v193, s[60:61] offset:320
	global_load_dwordx4 v[24:27], v193, s[60:61] offset:384
	global_load_dwordx4 v[28:31], v193, s[60:61] offset:448
	global_load_dwordx4 v[32:35], v192, s[62:63]
	global_load_dwordx4 v[36:39], v192, s[62:63] offset:1024
	global_load_dwordx4 v[40:43], v192, s[62:63] offset:2048
	global_load_dwordx4 v[44:47], v192, s[62:63] offset:3072
	global_load_dwordx4 v[48:51], v192, s[64:65] offset:-4096
	global_load_dwordx4 v[64:67], v192, s[64:65]
	global_load_dwordx4 v[52:55], v192, s[64:65] offset:-3072
	global_load_dwordx4 v[68:71], v192, s[64:65] offset:1024
	global_load_dwordx4 v[56:59], v192, s[64:65] offset:-2048
	global_load_dwordx4 v[72:75], v192, s[64:65] offset:2048
	global_load_dwordx4 v[60:63], v192, s[64:65] offset:-1024
	global_load_dwordx4 v[76:79], v192, s[64:65] offset:3072
	v_mov_b32_e32 v216, 0
	v_mov_b32_e32 v217, 0
	v_mov_b32_e32 v218, 0
	v_mov_b32_e32 v219, 0
	v_mov_b32_e32 v80, 0
	v_mov_b32_e32 v81, 0
	v_mov_b32_e32 v82, 0
	v_mov_b32_e32 v83, 0
	v_mov_b32_e32 v84, 0
	v_mov_b32_e32 v85, 0
	v_mov_b32_e32 v86, 0
	v_mov_b32_e32 v87, 0
	v_mov_b32_e32 v88, 0
	v_mov_b32_e32 v89, 0
	v_mov_b32_e32 v90, 0
	v_mov_b32_e32 v91, 0
	v_mov_b32_e32 v92, 0
	v_mov_b32_e32 v93, 0
	v_mov_b32_e32 v94, 0
	v_mov_b32_e32 v95, 0
	v_mov_b32_e32 v96, 0
	v_mov_b32_e32 v97, 0
	v_mov_b32_e32 v98, 0
	v_mov_b32_e32 v99, 0
	v_mov_b32_e32 v100, 0
	v_mov_b32_e32 v101, 0
	v_mov_b32_e32 v102, 0
	v_mov_b32_e32 v103, 0
	v_mov_b32_e32 v104, 0
	v_mov_b32_e32 v105, 0
	v_mov_b32_e32 v106, 0
	v_mov_b32_e32 v107, 0
	v_mov_b32_e32 v108, 0
	v_mov_b32_e32 v109, 0
	v_mov_b32_e32 v110, 0
	v_mov_b32_e32 v111, 0
	v_lshlrev_b32_e32 v213, 4, v198
	ds_write_b128 v213, v[216:219] offset:0
	ds_write_b128 v213, v[216:219] offset:8192
	ds_write_b128 v213, v[216:219] offset:16384
	ds_write_b128 v213, v[216:219] offset:24576
	ds_write_b128 v213, v[216:219] offset:32768
	s_waitcnt vmcnt(20)
	ds_write_b128 v201, v[176:179]
	ds_write_b128 v201, v[180:183] offset:128
	v_add_u32_e32 v201, 17408, v201
	s_add_u32 s60, s60, 0x40000
	s_addc_u32 s61, s61, 0
	s_add_u32 s62, s62, 0x8000
	s_addc_u32 s63, s63, 0
	s_add_u32 s64, s64, 0x10000
	s_addc_u32 s65, s65, 0
	s_add_u32 s66, s66, 0x100
	s_addc_u32 s67, s67, 0
	s_mov_b32 s70, 0
	s_mov_b32 s80, 33792
	s_mov_b32 s81, 17408
	s_waitcnt vmcnt(0) lgkmcnt(0)
	s_barrier
.Lscan_chunk:
	global_load_dwordx4 v[176:179], v194, s[66:67]
	global_load_dwordx4 v[180:183], v194, s[66:67] offset:128
	ds_read_b128 v[144:147], v196 offset:0
	ds_read_b128 v[148:151], v196 offset:8448
	ds_read_b128 v[152:155], v196 offset:16896
	ds_read_b128 v[156:159], v196 offset:25344
	ds_read_b128 v[160:163], v196 offset:64
	ds_read_b128 v[164:167], v196 offset:8512
	ds_read_b128 v[168:171], v196 offset:16960
	s_waitcnt lgkmcnt(6)
	s_waitcnt vmcnt(23)
	v_mfma_f32_16x16x32_bf16 v[112:115], v[144:147], v[0:3], 0
	ds_read_b128 v[172:175], v196 offset:25408
	s_waitcnt lgkmcnt(6)
	v_mfma_f32_16x16x32_bf16 v[116:119], v[148:151], v[0:3], 0
	ds_read_b128 v[144:147], v196 offset:128
	s_waitcnt lgkmcnt(6)
	v_mfma_f32_16x16x32_bf16 v[120:123], v[152:155], v[0:3], 0
	ds_read_b128 v[148:151], v196 offset:8576
	s_waitcnt lgkmcnt(6)
	v_mfma_f32_16x16x32_bf16 v[124:127], v[156:159], v[0:3], 0
	global_load_dwordx4 v[0:3], v193, s[60:61]
	ds_read_b128 v[152:155], v196 offset:17024
	s_waitcnt lgkmcnt(6)
	s_waitcnt vmcnt(23)
	v_mfma_f32_16x16x32_bf16 v[112:115], v[160:163], v[4:7], v[112:115]
	ds_read_b128 v[156:159], v196 offset:25472
	s_waitcnt lgkmcnt(6)
	v_mfma_f32_16x16x32_bf16 v[116:119], v[164:167], v[4:7], v[116:119]
	ds_read_b128 v[160:163], v196 offset:192
	s_waitcnt lgkmcnt(6)
	v_mfma_f32_16x16x32_bf16 v[120:123], v[168:171], v[4:7], v[120:123]
	ds_read_b128 v[164:167], v196 offset:8640
	s_waitcnt lgkmcnt(6)
	v_mfma_f32_16x16x32_bf16 v[124:127], v[172:175], v[4:7], v[124:127]
	global_load_dwordx4 v[4:7], v193, s[60:61] offset:64
	ds_read_b128 v[168:171], v196 offset:17088
	s_waitcnt lgkmcnt(6)
	s_waitcnt vmcnt(23)
	v_mfma_f32_16x16x32_bf16 v[112:115], v[144:147], v[8:11], v[112:115]
	ds_read_b128 v[172:175], v196 offset:25536
	s_waitcnt lgkmcnt(6)
	v_mfma_f32_16x16x32_bf16 v[116:119], v[148:151], v[8:11], v[116:119]
	ds_read_b128 v[144:147], v196 offset:256
	s_waitcnt lgkmcnt(6)
	v_mfma_f32_16x16x32_bf16 v[120:123], v[152:155], v[8:11], v[120:123]
	ds_read_b128 v[148:151], v196 offset:8704
	s_waitcnt lgkmcnt(6)
	v_mfma_f32_16x16x32_bf16 v[124:127], v[156:159], v[8:11], v[124:127]
	global_load_dwordx4 v[8:11], v193, s[60:61] offset:128
	ds_read_b128 v[152:155], v196 offset:17152
	s_waitcnt lgkmcnt(6)
	s_waitcnt vmcnt(23)
	v_mfma_f32_16x16x32_bf16 v[112:115], v[160:163], v[12:15], v[112:115]
	ds_read_b128 v[156:159], v196 offset:25600
	s_waitcnt lgkmcnt(6)
	v_mfma_f32_16x16x32_bf16 v[116:119], v[164:167], v[12:15], v[116:119]
	ds_read_b128 v[160:163], v196 offset:320
	s_waitcnt lgkmcnt(6)
	v_mfma_f32_16x16x32_bf16 v[120:123], v[168:171], v[12:15], v[120:123]
	ds_read_b128 v[164:167], v196 offset:8768
	s_waitcnt lgkmcnt(6)
	v_mfma_f32_16x16x32_bf16 v[124:127], v[172:175], v[12:15], v[124:127]
	global_load_dwordx4 v[12:15], v193, s[60:61] offset:192
	ds_read_b128 v[168:171], v196 offset:17216
	s_waitcnt lgkmcnt(6)
	s_waitcnt vmcnt(23)
	v_mfma_f32_16x16x32_bf16 v[112:115], v[144:147], v[16:19], v[112:115]
	ds_read_b128 v[172:175], v196 offset:25664
	s_waitcnt lgkmcnt(6)
	v_mfma_f32_16x16x32_bf16 v[116:119], v[148:151], v[16:19], v[116:119]
	ds_read_b128 v[144:147], v196 offset:384
	s_waitcnt lgkmcnt(6)
	v_mfma_f32_16x16x32_bf16 v[120:123], v[152:155], v[16:19], v[120:123]
	ds_read_b128 v[148:151], v196 offset:8832
	s_waitcnt lgkmcnt(6)
	v_mfma_f32_16x16x32_bf16 v[124:127], v[156:159], v[16:19], v[124:127]
	global_load_dwordx4 v[16:19], v193, s[60:61] offset:256
	ds_read_b128 v[152:155], v196 offset:17280
	s_waitcnt lgkmcnt(6)
	s_waitcnt vmcnt(23)
	v_mfma_f32_16x16x32_bf16 v[112:115], v[160:163], v[20:23], v[112:115]
	ds_read_b128 v[156:159], v196 offset:25728
	s_waitcnt lgkmcnt(6)
	v_mfma_f32_16x16x32_bf16 v[116:119], v[164:167], v[20:23], v[116:119]
	ds_read_b128 v[160:163], v196 offset:448
	s_waitcnt lgkmcnt(6)
	v_mfma_f32_16x16x32_bf16 v[120:123], v[168:171], v[20:23], v[120:123]
	ds_read_b128 v[164:167], v196 offset:8896
	s_waitcnt lgkmcnt(6)
	v_mfma_f32_16x16x32_bf16 v[124:127], v[172:175], v[20:23], v[124:127]
	global_load_dwordx4 v[20:23], v193, s[60:61] offset:320
	ds_read_b128 v[168:171], v196 offset:17344
	s_waitcnt lgkmcnt(6)
	s_waitcnt vmcnt(23)
	v_mfma_f32_16x16x32_bf16 v[112:115], v[144:147], v[24:27], v[112:115]
	ds_read_b128 v[172:175], v196 offset:25792
	s_waitcnt lgkmcnt(6)
	v_mfma_f32_16x16x32_bf16 v[116:119], v[148:151], v[24:27], v[116:119]
	ds_read_b128 v[144:147], v197 offset:0
	s_waitcnt lgkmcnt(6)
	v_mfma_f32_16x16x32_bf16 v[120:123], v[152:155], v[24:27], v[120:123]
	ds_read_b128 v[148:151], v197 offset:4352
	s_waitcnt lgkmcnt(6)
	v_mfma_f32_16x16x32_bf16 v[124:127], v[156:159], v[24:27], v[124:127]
	global_load_dwordx4 v[24:27], v193, s[60:61] offset:384
	ds_read_b128 v[152:155], v197 offset:8704
	s_waitcnt lgkmcnt(6)
	s_waitcnt vmcnt(23)
	v_mfma_f32_16x16x32_bf16 v[112:115], v[160:163], v[28:31], v[112:115]
	ds_read_b128 v[156:159], v197 offset:13056
	s_waitcnt lgkmcnt(6)
	v_mfma_f32_16x16x32_bf16 v[116:119], v[164:167], v[28:31], v[116:119]
	ds_read_b128 v[160:163], v197 offset:64
	s_waitcnt lgkmcnt(6)
	v_mfma_f32_16x16x32_bf16 v[120:123], v[168:171], v[28:31], v[120:123]
	ds_read_b128 v[164:167], v197 offset:4416
	s_waitcnt lgkmcnt(6)
	v_mfma_f32_16x16x32_bf16 v[124:127], v[172:175], v[28:31], v[124:127]
	global_load_dwordx4 v[28:31], v193, s[60:61] offset:448
	ds_read_b128 v[168:171], v197 offset:8768
	s_waitcnt lgkmcnt(6)
	s_waitcnt vmcnt(23)
	v_mfma_f32_16x16x32_bf16 v[128:131], v[144:147], v[32:35], 0
	ds_read_b128 v[172:175], v197 offset:13120
	s_waitcnt lgkmcnt(6)
	v_mfma_f32_16x16x32_bf16 v[132:135], v[148:151], v[32:35], 0
	ds_read_b128 v[144:147], v197 offset:128
	s_waitcnt lgkmcnt(6)
	v_mfma_f32_16x16x32_bf16 v[136:139], v[152:155], v[32:35], 0
	ds_read_b128 v[148:151], v197 offset:4480
	s_waitcnt lgkmcnt(6)
	v_mfma_f32_16x16x32_bf16 v[140:143], v[156:159], v[32:35], 0
	global_load_dwordx4 v[32:35], v192, s[62:63]
	ds_read_b128 v[152:155], v197 offset:8832
	s_waitcnt lgkmcnt(6)
	s_waitcnt vmcnt(23)
	v_mfma_f32_16x16x32_bf16 v[128:131], v[160:163], v[36:39], v[128:131]
	ds_read_b128 v[156:159], v197 offset:13184
	s_waitcnt lgkmcnt(6)
	v_mfma_f32_16x16x32_bf16 v[132:135], v[164:167], v[36:39], v[132:135]
	ds_read_b128 v[160:163], v197 offset:192
	s_waitcnt lgkmcnt(6)
	v_mfma_f32_16x16x32_bf16 v[136:139], v[168:171], v[36:39], v[136:139]
	ds_read_b128 v[164:167], v197 offset:4544
	s_waitcnt lgkmcnt(6)
	v_mfma_f32_16x16x32_bf16 v[140:143], v[172:175], v[36:39], v[140:143]
	global_load_dwordx4 v[36:39], v192, s[62:63] offset:1024
	ds_read_b128 v[168:171], v197 offset:8896
	s_waitcnt lgkmcnt(6)
	s_waitcnt vmcnt(23)
	v_mfma_f32_16x16x32_bf16 v[128:131], v[144:147], v[40:43], v[128:131]
	ds_read_b128 v[172:175], v197 offset:13248
	s_waitcnt lgkmcnt(6)
	v_mfma_f32_16x16x32_bf16 v[132:135], v[148:151], v[40:43], v[132:135]
	s_waitcnt lgkmcnt(5)
	v_mfma_f32_16x16x32_bf16 v[136:139], v[152:155], v[40:43], v[136:139]
	s_waitcnt lgkmcnt(4)
	v_mfma_f32_16x16x32_bf16 v[140:143], v[156:159], v[40:43], v[140:143]
	global_load_dwordx4 v[40:43], v192, s[62:63] offset:2048
	s_waitcnt lgkmcnt(3)
	s_waitcnt vmcnt(23)
	v_mfma_f32_16x16x32_bf16 v[128:131], v[160:163], v[44:47], v[128:131]
	s_waitcnt lgkmcnt(2)
	v_mfma_f32_16x16x32_bf16 v[132:135], v[164:167], v[44:47], v[132:135]
	s_waitcnt lgkmcnt(1)
	v_mfma_f32_16x16x32_bf16 v[136:139], v[168:171], v[44:47], v[136:139]
	s_waitcnt lgkmcnt(0)
	v_mfma_f32_16x16x32_bf16 v[140:143], v[172:175], v[44:47], v[140:143]
	global_load_dwordx4 v[44:47], v192, s[62:63] offset:3072
	s_nop 7
	v_pk_fma_f32 v[112:113], v[112:113], v[202:203], v[128:129]
	v_pk_fma_f32 v[114:115], v[114:115], v[202:203], v[130:131]
	v_pk_fma_f32 v[116:117], v[116:117], v[202:203], v[132:133]
	v_pk_fma_f32 v[118:119], v[118:119], v[202:203], v[134:135]
	v_pk_fma_f32 v[120:121], v[120:121], v[202:203], v[136:137]
	v_pk_fma_f32 v[122:123], v[122:123], v[202:203], v[138:139]
	v_pk_fma_f32 v[124:125], v[124:125], v[202:203], v[140:141]
	v_pk_fma_f32 v[126:127], v[126:127], v[202:203], v[142:143]
	v_cvt_pk_bf16_f32 v184, v112, v113
	v_cvt_pk_bf16_f32 v185, v114, v115
	v_cvt_pk_bf16_f32 v186, v116, v117
	v_cvt_pk_bf16_f32 v187, v118, v119
	v_cvt_pk_bf16_f32 v188, v120, v121
	v_cvt_pk_bf16_f32 v189, v122, v123
	v_cvt_pk_bf16_f32 v190, v124, v125
	v_cvt_pk_bf16_f32 v191, v126, v127
	ds_write_b64 v214, v[184:185]
	ds_write_b64 v214, v[186:187] offset:32
	ds_write_b64 v214, v[188:189] offset:64
	ds_write_b64 v214, v[190:191] offset:96
	s_waitcnt lgkmcnt(0)
	ds_read_b128 v[144:147], v215
	ds_read_b128 v[148:151], v215 offset:1152
	s_waitcnt lgkmcnt(0)
	global_store_dwordx4 v195, v[144:147], s[68:69]
	global_store_dwordx4 v220, v[148:151], s[68:69]
	v_pk_mul_f32 v[80:81], v[80:81], v[204:205]
	v_pk_mul_f32 v[82:83], v[82:83], v[204:205]
	v_pk_mul_f32 v[84:85], v[84:85], v[204:205]
	v_pk_mul_f32 v[86:87], v[86:87], v[204:205]
	v_pk_mul_f32 v[88:89], v[88:89], v[204:205]
	v_pk_mul_f32 v[90:91], v[90:91], v[204:205]
	v_pk_mul_f32 v[92:93], v[92:93], v[204:205]
	v_pk_mul_f32 v[94:95], v[94:95], v[204:205]
	v_pk_mul_f32 v[96:97], v[96:97], v[204:205]
	v_pk_mul_f32 v[98:99], v[98:99], v[204:205]
	v_pk_mul_f32 v[100:101], v[100:101], v[204:205]
	v_pk_mul_f32 v[102:103], v[102:103], v[204:205]
	v_pk_mul_f32 v[104:105], v[104:105], v[204:205]
	v_pk_mul_f32 v[106:107], v[106:107], v[204:205]
	v_pk_mul_f32 v[108:109], v[108:109], v[204:205]
	v_pk_mul_f32 v[110:111], v[110:111], v[204:205]
	ds_read_b128 v[144:147], v197 offset:0
	ds_read_b128 v[148:151], v197 offset:4352
	ds_read_b128 v[152:155], v197 offset:8704
	ds_read_b128 v[156:159], v197 offset:13056
	ds_read_b128 v[160:163], v197 offset:64
	ds_read_b128 v[164:167], v197 offset:4416
	ds_read_b128 v[168:171], v197 offset:8768
	s_waitcnt lgkmcnt(6)
	s_waitcnt vmcnt(22)
	v_mfma_f32_16x16x32_bf16 v[80:83], v[48:51], v[144:147], v[80:83]
	v_mfma_f32_16x16x32_bf16 v[96:99], v[64:67], v[144:147], v[96:99]
	ds_read_b128 v[172:175], v197 offset:13120
	s_waitcnt lgkmcnt(6)
	v_mfma_f32_16x16x32_bf16 v[84:87], v[48:51], v[148:151], v[84:87]
	v_mfma_f32_16x16x32_bf16 v[100:103], v[64:67], v[148:151], v[100:103]
	ds_read_b128 v[144:147], v197 offset:128
	s_waitcnt lgkmcnt(6)
	v_mfma_f32_16x16x32_bf16 v[88:91], v[48:51], v[152:155], v[88:91]
	v_mfma_f32_16x16x32_bf16 v[104:107], v[64:67], v[152:155], v[104:107]
	ds_read_b128 v[148:151], v197 offset:4480
	s_waitcnt lgkmcnt(6)
	v_mfma_f32_16x16x32_bf16 v[92:95], v[48:51], v[156:159], v[92:95]
	v_mfma_f32_16x16x32_bf16 v[108:111], v[64:67], v[156:159], v[108:111]
	global_load_dwordx4 v[48:51], v192, s[64:65] offset:-4096
	global_load_dwordx4 v[64:67], v192, s[64:65]
	ds_read_b128 v[152:155], v197 offset:8832
	s_waitcnt lgkmcnt(6)
	s_waitcnt vmcnt(22)
	v_mfma_f32_16x16x32_bf16 v[80:83], v[52:55], v[160:163], v[80:83]
	v_mfma_f32_16x16x32_bf16 v[96:99], v[68:71], v[160:163], v[96:99]
	ds_read_b128 v[156:159], v197 offset:13184
	s_waitcnt lgkmcnt(6)
	v_mfma_f32_16x16x32_bf16 v[84:87], v[52:55], v[164:167], v[84:87]
	v_mfma_f32_16x16x32_bf16 v[100:103], v[68:71], v[164:167], v[100:103]
	ds_read_b128 v[160:163], v197 offset:192
	s_waitcnt lgkmcnt(6)
	v_mfma_f32_16x16x32_bf16 v[88:91], v[52:55], v[168:171], v[88:91]
	v_mfma_f32_16x16x32_bf16 v[104:107], v[68:71], v[168:171], v[104:107]
	ds_read_b128 v[164:167], v197 offset:4544
	s_waitcnt lgkmcnt(6)
	v_mfma_f32_16x16x32_bf16 v[92:95], v[52:55], v[172:175], v[92:95]
	v_mfma_f32_16x16x32_bf16 v[108:111], v[68:71], v[172:175], v[108:111]
	global_load_dwordx4 v[52:55], v192, s[64:65] offset:-3072
	global_load_dwordx4 v[68:71], v192, s[64:65] offset:1024
	ds_read_b128 v[168:171], v197 offset:8896
	s_waitcnt lgkmcnt(6)
	s_waitcnt vmcnt(22)
	v_mfma_f32_16x16x32_bf16 v[80:83], v[56:59], v[144:147], v[80:83]
	v_mfma_f32_16x16x32_bf16 v[96:99], v[72:75], v[144:147], v[96:99]
	ds_read_b128 v[172:175], v197 offset:13248
	s_waitcnt lgkmcnt(6)
	v_mfma_f32_16x16x32_bf16 v[84:87], v[56:59], v[148:151], v[84:87]
	v_mfma_f32_16x16x32_bf16 v[100:103], v[72:75], v[148:151], v[100:103]
	s_waitcnt lgkmcnt(5)
	v_mfma_f32_16x16x32_bf16 v[88:91], v[56:59], v[152:155], v[88:91]
	v_mfma_f32_16x16x32_bf16 v[104:107], v[72:75], v[152:155], v[104:107]
	s_waitcnt lgkmcnt(4)
	v_mfma_f32_16x16x32_bf16 v[92:95], v[56:59], v[156:159], v[92:95]
	v_mfma_f32_16x16x32_bf16 v[108:111], v[72:75], v[156:159], v[108:111]
	global_load_dwordx4 v[56:59], v192, s[64:65] offset:-2048
	global_load_dwordx4 v[72:75], v192, s[64:65] offset:2048
	s_waitcnt lgkmcnt(3)
	s_waitcnt vmcnt(22)
	v_mfma_f32_16x16x32_bf16 v[80:83], v[60:63], v[160:163], v[80:83]
	v_mfma_f32_16x16x32_bf16 v[96:99], v[76:79], v[160:163], v[96:99]
	s_waitcnt lgkmcnt(2)
	v_mfma_f32_16x16x32_bf16 v[84:87], v[60:63], v[164:167], v[84:87]
	v_mfma_f32_16x16x32_bf16 v[100:103], v[76:79], v[164:167], v[100:103]
	s_waitcnt lgkmcnt(1)
	v_mfma_f32_16x16x32_bf16 v[88:91], v[60:63], v[168:171], v[88:91]
	v_mfma_f32_16x16x32_bf16 v[104:107], v[76:79], v[168:171], v[104:107]
	s_waitcnt lgkmcnt(0)
	v_mfma_f32_16x16x32_bf16 v[92:95], v[60:63], v[172:175], v[92:95]
	v_mfma_f32_16x16x32_bf16 v[108:111], v[76:79], v[172:175], v[108:111]
	global_load_dwordx4 v[60:63], v192, s[64:65] offset:-1024
	global_load_dwordx4 v[76:79], v192, s[64:65] offset:3072
	s_nop 7
	v_cvt_pk_bf16_f32 v144, v80, v81
	v_cvt_pk_bf16_f32 v145, v82, v83
	ds_write_b64 v200, v[144:145] offset:0
	v_cvt_pk_bf16_f32 v148, v84, v85
	v_cvt_pk_bf16_f32 v149, v86, v87
	ds_write_b64 v200, v[148:149] offset:8448
	v_cvt_pk_bf16_f32 v152, v88, v89
	v_cvt_pk_bf16_f32 v153, v90, v91
	ds_write_b64 v200, v[152:153] offset:16896
	v_cvt_pk_bf16_f32 v156, v92, v93
	v_cvt_pk_bf16_f32 v157, v94, v95
	ds_write_b64 v200, v[156:157] offset:25344
	v_cvt_pk_bf16_f32 v160, v96, v97
	v_cvt_pk_bf16_f32 v161, v98, v99
	ds_write_b64 v200, v[160:161] offset:32
	v_cvt_pk_bf16_f32 v164, v100, v101
	v_cvt_pk_bf16_f32 v165, v102, v103
	ds_write_b64 v200, v[164:165] offset:8480
	v_cvt_pk_bf16_f32 v168, v104, v105
	v_cvt_pk_bf16_f32 v169, v106, v107
	ds_write_b64 v200, v[168:169] offset:16928
	v_cvt_pk_bf16_f32 v172, v108, v109
	v_cvt_pk_bf16_f32 v173, v110, v111
	ds_write_b64 v200, v[172:173] offset:25376
	s_waitcnt vmcnt(22)
	ds_write_b128 v201, v[176:179]
	ds_write_b128 v201, v[180:183] offset:128
	v_add_u32_e32 v196, s80, v196
	v_subrev_u32_e32 v200, s80, v200
	v_add_u32_e32 v197, s81, v197
	v_subrev_u32_e32 v201, s81, v201
	s_sub_u32 s80, 0, s80
	s_sub_u32 s81, 0, s81
	s_add_u32 s68, s68, 0x80000
	s_addc_u32 s69, s69, 0
	s_add_u32 s70, s70, 1
	s_cmp_lt_u32 s70, 31
	s_cselect_b32 s83, 1, 0
	s_lshl_b32 s76, s83, 18
	s_add_u32 s60, s60, s76
	s_addc_u32 s61, s61, 0
	s_lshl_b32 s76, s83, 15
	s_add_u32 s62, s62, s76
	s_addc_u32 s63, s63, 0
	s_lshl_b32 s76, s83, 16
	s_add_u32 s64, s64, s76
	s_addc_u32 s65, s65, 0
	s_lshl_b32 s76, s83, 8
	s_add_u32 s66, s66, s76
	s_addc_u32 s67, s67, 0
	s_waitcnt lgkmcnt(0)
	s_barrier
	s_cmp_lt_u32 s70, 32
	s_cbranch_scc1 .Lscan_chunk
	s_waitcnt vmcnt(0)
	global_store_dword v206, v80, s[44:45]
	global_store_dword v207, v81, s[44:45]
	global_store_dword v208, v82, s[44:45]
	global_store_dword v209, v83, s[44:45]
	global_store_dword v206, v84, s[44:45] offset:64
	global_store_dword v207, v85, s[44:45] offset:64
	global_store_dword v208, v86, s[44:45] offset:64
	global_store_dword v209, v87, s[44:45] offset:64
	global_store_dword v206, v88, s[44:45] offset:128
	global_store_dword v207, v89, s[44:45] offset:128
	global_store_dword v208, v90, s[44:45] offset:128
	global_store_dword v209, v91, s[44:45] offset:128
	global_store_dword v206, v92, s[44:45] offset:192
	global_store_dword v207, v93, s[44:45] offset:192
	global_store_dword v208, v94, s[44:45] offset:192
	global_store_dword v209, v95, s[44:45] offset:192
	global_store_dword v206, v96, s[46:47]
	global_store_dword v207, v97, s[46:47]
	global_store_dword v208, v98, s[46:47]
	global_store_dword v209, v99, s[46:47]
	global_store_dword v206, v100, s[46:47] offset:64
	global_store_dword v207, v101, s[46:47] offset:64
	global_store_dword v208, v102, s[46:47] offset:64
	global_store_dword v209, v103, s[46:47] offset:64
	global_store_dword v206, v104, s[46:47] offset:128
	global_store_dword v207, v105, s[46:47] offset:128
	global_store_dword v208, v106, s[46:47] offset:128
	global_store_dword v209, v107, s[46:47] offset:128
	global_store_dword v206, v108, s[46:47] offset:192
	global_store_dword v207, v109, s[46:47] offset:192
	global_store_dword v208, v110, s[46:47] offset:192
	global_store_dword v209, v111, s[46:47] offset:192
